# LayerNorm: adaLN shift/scale loaded first in the iteration (v216-247), LN gamma/beta loaded once per iteration (v138-169); no per-chunk load+vmcnt(0) pairs, counted waits for rows 1-3 on the l==0 path
# baseline (speedup 1.0000x reference)
.LBB0_110:
	s_waitcnt vmcnt(12)
	v_lshrrev_b32_e32 v7, 20, v7
	v_add_u32_e32 v7, v98, v7
	v_ashrrev_i32_e32 v7, 12, v7
	v_add_u32_e32 v7, s2, v7
	v_mul_hi_i32_i24_e32 v39, 0x3000, v7
	v_mul_i32_i24_e32 v38, 0x3000, v7
	v_lshl_add_u64 v[40:41], s[84:85], 0, v[38:39]
	v_lshl_add_u64 v[38:39], v[40:41], 0, s[8:9]
	v_lshl_add_u64 v[40:41], v[40:41], 0, v[94:95]
	v_lshl_add_u64 v[46:47], v[38:39], 0, v[94:95]
	v_add_f32_e32 v15, v32, v33
	v_add_f32_e32 v19, v34, v35
	v_add_f32_e32 v15, v15, v19
	v_add_f32_e32 v19, v28, v29
	v_add_f32_e32 v36, v30, v31
	v_add_f32_e32 v15, 0, v15
	v_add_f32_e32 v19, v19, v36
	v_add_f32_e32 v15, v19, v15
	v_add_f32_e32 v19, v24, v25
	v_add_f32_e32 v36, v26, v27
	v_add_f32_e32 v19, v19, v36
	v_add_f32_e32 v15, v19, v15
	v_add_f32_e32 v19, v20, v21
	v_add_f32_e32 v36, v22, v23
	v_add_f32_e32 v19, v19, v36
	v_add_f32_e32 v15, v19, v15
	s_add_i32 s3, s3, s26
	v_add_u32_e32 v86, s75, v86
	v_add_f32_dpp v15, v15, v15 row_ror:8 row_mask:0xf bank_mask:0xf bound_ctrl:1
	s_cmpk_lt_i32 s3, 0x400
	s_nop 0
	v_mov_b64_e32 v[42:43], v[216:217]
	v_mov_b64_e32 v[44:45], v[218:219]
	v_mov_b64_e32 v[46:47], v[232:233]
	v_mov_b64_e32 v[48:49], v[234:235]
	v_pk_add_f32 v[48:49], v[48:49], 1.0 op_sel_hi:[1,0]
	v_add_f32_dpp v15, v15, v15 row_ror:4 row_mask:0xf bank_mask:0xf bound_ctrl:1
	v_pk_add_f32 v[46:47], v[46:47], 1.0 op_sel_hi:[1,0]
	s_nop 0
	v_add_f32_dpp v15, v15, v15 row_ror:2 row_mask:0xf bank_mask:0xf bound_ctrl:1
	s_nop 1
	v_add_f32_dpp v15, v15, v15 row_ror:1 row_mask:0xf bank_mask:0xf bound_ctrl:1
	v_mov_b32_e32 v19, v15
	s_nop 1
	v_permlane16_swap_b32_e32 v15, v19
	v_add_f32_e32 v15, v15, v19
	v_mov_b32_e32 v19, v15
	s_nop 1
	v_permlane32_swap_b32_e32 v15, v19
	v_add_f32_e32 v15, v15, v19
	v_fmamk_f32 v37, v15, 0xba800000, v35
	v_fmac_f32_e32 v33, 0xba800000, v15
	v_fmamk_f32 v36, v15, 0xba800000, v34
	v_fmamk_f32 v32, v15, 0xba800000, v32
	v_mul_f32_e32 v19, v33, v33
	v_mul_f32_e32 v34, v37, v37
	v_fmac_f32_e32 v19, v32, v32
	v_fmac_f32_e32 v34, v36, v36
	v_fmamk_f32 v35, v15, 0xba800000, v31
	v_fmac_f32_e32 v29, 0xba800000, v15
	v_add_f32_e32 v19, v19, v34
	v_fmamk_f32 v34, v15, 0xba800000, v30
	v_fmamk_f32 v28, v15, 0xba800000, v28
	v_mul_f32_e32 v30, v29, v29
	v_mul_f32_e32 v31, v35, v35
	v_fmac_f32_e32 v30, v28, v28
	v_fmac_f32_e32 v31, v34, v34
	v_add_f32_e32 v30, v30, v31
	v_fmamk_f32 v31, v15, 0xba800000, v27
	v_fmac_f32_e32 v25, 0xba800000, v15
	v_add_f32_e32 v19, v19, v30
	v_fmamk_f32 v30, v15, 0xba800000, v26
	v_fmamk_f32 v24, v15, 0xba800000, v24
	v_mul_f32_e32 v26, v25, v25
	v_mul_f32_e32 v27, v31, v31
	v_fmac_f32_e32 v26, v24, v24
	v_fmac_f32_e32 v27, v30, v30
	v_add_f32_e32 v26, v26, v27
	v_fmamk_f32 v23, v15, 0xba800000, v23
	v_fmac_f32_e32 v21, 0xba800000, v15
	v_add_f32_e32 v19, v26, v19
	v_fmamk_f32 v22, v15, 0xba800000, v22
	v_fmamk_f32 v20, v15, 0xba800000, v20
	v_mul_f32_e32 v15, v21, v21
	v_mul_f32_e32 v26, v23, v23
	v_fmac_f32_e32 v15, v20, v20
	v_fmac_f32_e32 v26, v22, v22
	v_add_f32_e32 v15, v15, v26
	v_add_f32_e32 v15, v15, v19
	s_nop 1
	v_add_f32_dpp v15, v15, v15 row_ror:8 row_mask:0xf bank_mask:0xf bound_ctrl:1
	s_nop 1
	v_add_f32_dpp v15, v15, v15 row_ror:4 row_mask:0xf bank_mask:0xf bound_ctrl:1
	s_nop 1
	v_add_f32_dpp v15, v15, v15 row_ror:2 row_mask:0xf bank_mask:0xf bound_ctrl:1
	s_nop 1
	v_add_f32_dpp v15, v15, v15 row_ror:1 row_mask:0xf bank_mask:0xf bound_ctrl:1
	v_mov_b32_e32 v19, v15
	s_nop 1
	v_permlane16_swap_b32_e32 v15, v19
	v_add_f32_e32 v15, v15, v19
	v_mov_b32_e32 v19, v15
	s_nop 1
	v_permlane32_swap_b32_e32 v15, v19
	v_add_f32_e32 v15, v15, v19
	v_fmamk_f32 v15, v15, 0x3a800000, v196
	v_cmp_gt_f32_e32 vcc, s22, v15
	v_mul_f32_e32 v19, 0x4b800000, v15
	s_nop 0
	v_cndmask_b32_e32 v15, v15, v19, vcc
	v_rsq_f32_e32 v15, v15
	s_nop 0
	v_mul_f32_e32 v19, 0x45800000, v15
	v_cndmask_b32_e32 v26, v15, v19, vcc
	v_pk_mul_f32 v[32:33], v[32:33], v[26:27] op_sel_hi:[1,0]
	v_pk_mul_f32 v[36:37], v[36:37], v[26:27] op_sel_hi:[1,0]
	v_pk_fma_f32 v[32:33], v[46:47], v[32:33], v[42:43]
	v_pk_fma_f32 v[36:37], v[48:49], v[36:37], v[44:45]
	v_cvt_pk_bf16_f32 v32, v32, v33
	v_cvt_pk_bf16_f32 v33, v36, v37
	v_lshl_add_u64 v[36:37], v[84:85], 0, v[96:97]
	global_store_dwordx2 v[36:37], v[32:33], off
	v_lshl_add_u64 v[32:33], v[38:39], 0, v[88:89]
	v_pk_mul_f32 v[28:29], v[28:29], v[26:27] op_sel_hi:[1,0]
	v_pk_mul_f32 v[32:33], v[34:35], v[26:27] op_sel_hi:[1,0]
	v_pk_mul_f32 v[24:25], v[24:25], v[26:27] op_sel_hi:[1,0]
	v_pk_mul_f32 v[20:21], v[20:21], v[26:27] op_sel_hi:[1,0]
	v_pk_mul_f32 v[22:23], v[22:23], v[26:27] op_sel_hi:[1,0]
	s_nop 0
	v_mov_b64_e32 v[42:43], v[220:221]
	v_mov_b64_e32 v[44:45], v[222:223]
	v_mov_b64_e32 v[46:47], v[236:237]
	v_mov_b64_e32 v[48:49], v[238:239]
	v_pk_add_f32 v[34:35], v[48:49], 1.0 op_sel_hi:[1,0]
	v_pk_add_f32 v[46:47], v[46:47], 1.0 op_sel_hi:[1,0]
	v_pk_fma_f32 v[32:33], v[34:35], v[32:33], v[44:45]
	v_pk_fma_f32 v[28:29], v[46:47], v[28:29], v[42:43]
	s_nop 0
	v_cvt_pk_bf16_f32 v28, v28, v29
	v_cvt_pk_bf16_f32 v29, v32, v33
	global_store_dwordx2 v[36:37], v[28:29], off offset:512
	v_lshl_add_u64 v[28:29], v[38:39], 0, v[90:91]
	v_pk_mul_f32 v[28:29], v[30:31], v[26:27] op_sel_hi:[1,0]
	s_nop 0
	v_mov_b64_e32 v[32:33], v[224:225]
	v_mov_b64_e32 v[34:35], v[226:227]
	v_mov_b64_e32 v[42:43], v[240:241]
	v_mov_b64_e32 v[44:45], v[242:243]
	v_pk_add_f32 v[30:31], v[44:45], 1.0 op_sel_hi:[1,0]
	v_pk_add_f32 v[42:43], v[42:43], 1.0 op_sel_hi:[1,0]
	v_pk_fma_f32 v[28:29], v[30:31], v[28:29], v[34:35]
	v_pk_fma_f32 v[24:25], v[42:43], v[24:25], v[32:33]
	s_nop 0
	v_cvt_pk_bf16_f32 v24, v24, v25
	v_cvt_pk_bf16_f32 v25, v28, v29
	global_store_dwordx2 v[36:37], v[24:25], off offset:1024
	v_lshl_add_u64 v[24:25], v[38:39], 0, v[92:93]
	s_nop 0
	v_mov_b64_e32 v[28:29], v[228:229]
	v_mov_b64_e32 v[30:31], v[230:231]
	v_mov_b64_e32 v[32:33], v[244:245]
	v_mov_b64_e32 v[34:35], v[246:247]
	v_pk_add_f32 v[24:25], v[34:35], 1.0 op_sel_hi:[1,0]
	v_pk_add_f32 v[26:27], v[32:33], 1.0 op_sel_hi:[1,0]
	v_pk_fma_f32 v[22:23], v[24:25], v[22:23], v[30:31]
	v_pk_fma_f32 v[20:21], v[26:27], v[20:21], v[28:29]
	s_nop 0
	v_cvt_pk_bf16_f32 v20, v20, v21
	v_cvt_pk_bf16_f32 v21, v22, v23
	global_store_dwordx2 v[36:37], v[20:21], off offset:1536
	s_cbranch_scc0 .LBB0_127
.LBB0_111:
	v_ashrrev_i32_e32 v186, 12, v86
	v_add_u32_e32 v186, s2, v186
	v_mul_hi_i32_i24_e32 v189, 0x3000, v186
	v_mul_i32_i24_e32 v188, 0x3000, v186
	v_lshl_add_u64 v[188:189], s[84:85], 0, v[188:189]
	v_mov_b32_e32 v186, v94
	v_mov_b32_e32 v187, v2
	v_lshl_add_u64 v[188:189], v[188:189], 0, v[186:187]
	s_mov_b64 s[100:101], 0x1000
	v_lshl_add_u64 v[186:187], v[188:189], 0, s[100:101]
	global_load_dwordx4 v[216:219], v[188:189], off
	global_load_dwordx4 v[220:223], v[188:189], off offset:1024
	global_load_dwordx4 v[224:227], v[188:189], off offset:2048
	global_load_dwordx4 v[228:231], v[188:189], off offset:3072
	global_load_dwordx4 v[232:235], v[186:187], off
	global_load_dwordx4 v[236:239], v[186:187], off offset:1024
	global_load_dwordx4 v[240:243], v[186:187], off offset:2048
	global_load_dwordx4 v[244:247], v[186:187], off offset:3072
	v_ashrrev_i32_e32 v87, 31, v86
	v_add_u32_e32 v110, 1, v86
	v_add_u32_e32 v104, 2, v86
	v_add_u32_e32 v98, 3, v86
	v_lshlrev_b64 v[116:117], 12, v[86:87]
	v_ashrrev_i32_e32 v111, 31, v110
	v_ashrrev_i32_e32 v105, 31, v104
	v_ashrrev_i32_e32 v99, 31, v98
	v_lshlrev_b64 v[112:113], 12, v[110:111]
	v_lshlrev_b64 v[106:107], 12, v[104:105]
	v_lshlrev_b64 v[100:101], 12, v[98:99]
	v_lshl_add_u64 v[130:131], v[4:5], 0, v[116:117]
	global_load_dwordx4 v[80:83], v[130:131], off nt
	global_load_dwordx4 v[76:79], v[130:131], off offset:1024 nt
	global_load_dwordx4 v[72:75], v[130:131], off offset:2048 nt
	global_load_dwordx4 v[68:71], v[130:131], off offset:3072 nt
	v_lshl_add_u64 v[130:131], v[4:5], 0, v[112:113]
	global_load_dwordx4 v[64:67], v[130:131], off nt
	global_load_dwordx4 v[60:63], v[130:131], off offset:1024 nt
	global_load_dwordx4 v[56:59], v[130:131], off offset:2048 nt
	global_load_dwordx4 v[52:55], v[130:131], off offset:3072 nt
	v_lshl_add_u64 v[130:131], v[4:5], 0, v[106:107]
	global_load_dwordx4 v[48:51], v[130:131], off nt
	global_load_dwordx4 v[44:47], v[130:131], off offset:1024 nt
	global_load_dwordx4 v[40:43], v[130:131], off offset:2048 nt
	global_load_dwordx4 v[36:39], v[130:131], off offset:3072 nt
	v_lshl_add_u64 v[130:131], v[4:5], 0, v[100:101]
	global_load_dwordx4 v[32:35], v[130:131], off nt
	global_load_dwordx4 v[28:31], v[130:131], off offset:1024 nt
	global_load_dwordx4 v[24:27], v[130:131], off offset:2048 nt
	global_load_dwordx4 v[20:23], v[130:131], off offset:3072 nt
	v_lshlrev_b64 v[114:115], 11, v[86:87]
	v_lshlrev_b64 v[108:109], 11, v[110:111]
	v_lshlrev_b64 v[102:103], 11, v[104:105]
	v_lshlrev_b64 v[96:97], 11, v[98:99]
	v_cmp_ne_u32_e64 s[38:39], 1, v3
	v_mov_b32_e32 v19, v111
	v_mov_b32_e32 v15, v105
	v_mov_b32_e32 v7, v99
	v_mov_b32_e32 v95, v2
	s_and_b64 vcc, exec, s[38:39]
	s_cbranch_vccnz .LBB0_119
	v_ashrrev_i32_e32 v132, 12, v86
	v_ashrrev_i32_e32 v133, 31, v132
	v_lshl_add_u64 v[132:133], s[12:13], 0, v[132:133]
	v_mov_b64_e32 v[134:135], s[84:85]
	s_movk_i32 s10, 0x3000
	v_mad_u64_u32 v[134:135], s[8:9], v132, s10, v[134:135]
	v_mad_i32_i24 v135, v133, s10, v135
	v_lshl_add_u64 v[134:135], v[134:135], 0, v[94:95]
	s_mov_b64 s[8:9], 0x2000
	v_lshl_add_u64 v[134:135], v[134:135], 0, s[8:9]
	global_load_dwordx4 v[170:173], v[134:135], off
	global_load_dwordx4 v[174:177], v[134:135], off offset:1024
	global_load_dwordx4 v[178:181], v[134:135], off offset:2048
	global_load_dwordx4 v[182:185], v[134:135], off offset:3072
	v_lshl_add_u64 v[136:137], v[0:1], 0, v[114:115]
	global_load_dwordx2 v[138:139], v[136:137], off nt
	global_load_dwordx2 v[140:141], v[136:137], off offset:512 nt
	global_load_dwordx2 v[142:143], v[136:137], off offset:1024 nt
	global_load_dwordx2 v[144:145], v[136:137], off offset:1536 nt
	v_lshl_add_u64 v[136:137], v[0:1], 0, v[108:109]
	global_load_dwordx2 v[146:147], v[136:137], off nt
	global_load_dwordx2 v[148:149], v[136:137], off offset:512 nt
	global_load_dwordx2 v[150:151], v[136:137], off offset:1024 nt
	global_load_dwordx2 v[152:153], v[136:137], off offset:1536 nt
	v_lshl_add_u64 v[136:137], v[0:1], 0, v[102:103]
	global_load_dwordx2 v[154:155], v[136:137], off nt
	global_load_dwordx2 v[156:157], v[136:137], off offset:512 nt
	global_load_dwordx2 v[158:159], v[136:137], off offset:1024 nt
	global_load_dwordx2 v[160:161], v[136:137], off offset:1536 nt
	v_lshl_add_u64 v[136:137], v[0:1], 0, v[96:97]
	global_load_dwordx2 v[162:163], v[136:137], off nt
	global_load_dwordx2 v[164:165], v[136:137], off offset:512 nt
	global_load_dwordx2 v[166:167], v[136:137], off offset:1024 nt
	global_load_dwordx2 v[168:169], v[136:137], off offset:1536 nt
	s_mov_b32 s8, 0x3fb504f3
	s_waitcnt vmcnt(15)
	v_pk_add_f32 v[172:173], v[172:173], 1.0 op_sel_hi:[1,0]
	v_pk_add_f32 v[170:171], v[170:171], 1.0 op_sel_hi:[1,0]
	v_lshlrev_b32_e32 v186, 16, v138
	v_and_b32_e32 v187, 0xffff0000, v138
	v_lshlrev_b32_e32 v188, 16, v139
	v_and_b32_e32 v189, 0xffff0000, v139
	v_pk_mul_f32 v[188:189], v[172:173], v[188:189]
	v_pk_mul_f32 v[186:187], v[170:171], v[186:187]
	v_pk_fma_f32 v[82:83], v[82:83], s[8:9], v[188:189] op_sel_hi:[1,0,1]
	v_pk_fma_f32 v[80:81], v[80:81], s[8:9], v[186:187] op_sel_hi:[1,0,1]
	s_waitcnt vmcnt(14)
	v_pk_add_f32 v[176:177], v[176:177], 1.0 op_sel_hi:[1,0]
	v_pk_add_f32 v[174:175], v[174:175], 1.0 op_sel_hi:[1,0]
	v_lshlrev_b32_e32 v186, 16, v140
	v_and_b32_e32 v187, 0xffff0000, v140
	v_lshlrev_b32_e32 v188, 16, v141
	v_and_b32_e32 v189, 0xffff0000, v141
	v_pk_mul_f32 v[188:189], v[176:177], v[188:189]
	v_pk_mul_f32 v[186:187], v[174:175], v[186:187]
	v_pk_fma_f32 v[78:79], v[78:79], s[8:9], v[188:189] op_sel_hi:[1,0,1]
	v_pk_fma_f32 v[76:77], v[76:77], s[8:9], v[186:187] op_sel_hi:[1,0,1]
	s_waitcnt vmcnt(13)
	v_pk_add_f32 v[180:181], v[180:181], 1.0 op_sel_hi:[1,0]
	v_pk_add_f32 v[178:179], v[178:179], 1.0 op_sel_hi:[1,0]
	v_lshlrev_b32_e32 v186, 16, v142
	v_and_b32_e32 v187, 0xffff0000, v142
	v_lshlrev_b32_e32 v188, 16, v143
	v_and_b32_e32 v189, 0xffff0000, v143
	v_pk_mul_f32 v[188:189], v[180:181], v[188:189]
	v_pk_mul_f32 v[186:187], v[178:179], v[186:187]
	v_pk_fma_f32 v[74:75], v[74:75], s[8:9], v[188:189] op_sel_hi:[1,0,1]
	v_pk_fma_f32 v[72:73], v[72:73], s[8:9], v[186:187] op_sel_hi:[1,0,1]
	s_waitcnt vmcnt(12)
	v_pk_add_f32 v[184:185], v[184:185], 1.0 op_sel_hi:[1,0]
	v_pk_add_f32 v[182:183], v[182:183], 1.0 op_sel_hi:[1,0]
	v_lshlrev_b32_e32 v186, 16, v144
	v_and_b32_e32 v187, 0xffff0000, v144
	v_lshlrev_b32_e32 v188, 16, v145
	v_and_b32_e32 v189, 0xffff0000, v145
	v_pk_mul_f32 v[188:189], v[184:185], v[188:189]
	v_pk_mul_f32 v[186:187], v[182:183], v[186:187]
	v_pk_fma_f32 v[70:71], v[70:71], s[8:9], v[188:189] op_sel_hi:[1,0,1]
	v_pk_fma_f32 v[68:69], v[68:69], s[8:9], v[186:187] op_sel_hi:[1,0,1]
	s_waitcnt vmcnt(11)
	v_lshlrev_b32_e32 v186, 16, v146
	v_and_b32_e32 v187, 0xffff0000, v146
	v_lshlrev_b32_e32 v188, 16, v147
	v_and_b32_e32 v189, 0xffff0000, v147
	v_pk_mul_f32 v[188:189], v[172:173], v[188:189]
	v_pk_mul_f32 v[186:187], v[170:171], v[186:187]
	v_pk_fma_f32 v[66:67], v[66:67], s[8:9], v[188:189] op_sel_hi:[1,0,1]
	v_pk_fma_f32 v[64:65], v[64:65], s[8:9], v[186:187] op_sel_hi:[1,0,1]
	s_waitcnt vmcnt(10)
	v_lshlrev_b32_e32 v186, 16, v148
	v_and_b32_e32 v187, 0xffff0000, v148
	v_lshlrev_b32_e32 v188, 16, v149
	v_and_b32_e32 v189, 0xffff0000, v149
	v_pk_mul_f32 v[188:189], v[176:177], v[188:189]
	v_pk_mul_f32 v[186:187], v[174:175], v[186:187]
	v_pk_fma_f32 v[62:63], v[62:63], s[8:9], v[188:189] op_sel_hi:[1,0,1]
	v_pk_fma_f32 v[60:61], v[60:61], s[8:9], v[186:187] op_sel_hi:[1,0,1]
	s_waitcnt vmcnt(9)
	v_lshlrev_b32_e32 v186, 16, v150
	v_and_b32_e32 v187, 0xffff0000, v150
	v_lshlrev_b32_e32 v188, 16, v151
	v_and_b32_e32 v189, 0xffff0000, v151
	v_pk_mul_f32 v[188:189], v[180:181], v[188:189]
	v_pk_mul_f32 v[186:187], v[178:179], v[186:187]
	v_pk_fma_f32 v[58:59], v[58:59], s[8:9], v[188:189] op_sel_hi:[1,0,1]
	v_pk_fma_f32 v[56:57], v[56:57], s[8:9], v[186:187] op_sel_hi:[1,0,1]
	s_waitcnt vmcnt(8)
	v_lshlrev_b32_e32 v186, 16, v152
	v_and_b32_e32 v187, 0xffff0000, v152
	v_lshlrev_b32_e32 v188, 16, v153
	v_and_b32_e32 v189, 0xffff0000, v153
	v_pk_mul_f32 v[188:189], v[184:185], v[188:189]
	v_pk_mul_f32 v[186:187], v[182:183], v[186:187]
	v_pk_fma_f32 v[54:55], v[54:55], s[8:9], v[188:189] op_sel_hi:[1,0,1]
	v_pk_fma_f32 v[52:53], v[52:53], s[8:9], v[186:187] op_sel_hi:[1,0,1]
	s_waitcnt vmcnt(7)
	v_lshlrev_b32_e32 v186, 16, v154
	v_and_b32_e32 v187, 0xffff0000, v154
	v_lshlrev_b32_e32 v188, 16, v155
	v_and_b32_e32 v189, 0xffff0000, v155
	v_pk_mul_f32 v[188:189], v[172:173], v[188:189]
	v_pk_mul_f32 v[186:187], v[170:171], v[186:187]
	v_pk_fma_f32 v[50:51], v[50:51], s[8:9], v[188:189] op_sel_hi:[1,0,1]
	v_pk_fma_f32 v[48:49], v[48:49], s[8:9], v[186:187] op_sel_hi:[1,0,1]
	s_waitcnt vmcnt(6)
	v_lshlrev_b32_e32 v186, 16, v156
	v_and_b32_e32 v187, 0xffff0000, v156
	v_lshlrev_b32_e32 v188, 16, v157
	v_and_b32_e32 v189, 0xffff0000, v157
	v_pk_mul_f32 v[188:189], v[176:177], v[188:189]
	v_pk_mul_f32 v[186:187], v[174:175], v[186:187]
	v_pk_fma_f32 v[46:47], v[46:47], s[8:9], v[188:189] op_sel_hi:[1,0,1]
	v_pk_fma_f32 v[44:45], v[44:45], s[8:9], v[186:187] op_sel_hi:[1,0,1]
	s_waitcnt vmcnt(5)
	v_lshlrev_b32_e32 v186, 16, v158
	v_and_b32_e32 v187, 0xffff0000, v158
	v_lshlrev_b32_e32 v188, 16, v159
	v_and_b32_e32 v189, 0xffff0000, v159
	v_pk_mul_f32 v[188:189], v[180:181], v[188:189]
	v_pk_mul_f32 v[186:187], v[178:179], v[186:187]
	v_pk_fma_f32 v[42:43], v[42:43], s[8:9], v[188:189] op_sel_hi:[1,0,1]
	v_pk_fma_f32 v[40:41], v[40:41], s[8:9], v[186:187] op_sel_hi:[1,0,1]
	s_waitcnt vmcnt(4)
	v_lshlrev_b32_e32 v186, 16, v160
	v_and_b32_e32 v187, 0xffff0000, v160
	v_lshlrev_b32_e32 v188, 16, v161
	v_and_b32_e32 v189, 0xffff0000, v161
	v_pk_mul_f32 v[188:189], v[184:185], v[188:189]
	v_pk_mul_f32 v[186:187], v[182:183], v[186:187]
	v_pk_fma_f32 v[38:39], v[38:39], s[8:9], v[188:189] op_sel_hi:[1,0,1]
	v_pk_fma_f32 v[36:37], v[36:37], s[8:9], v[186:187] op_sel_hi:[1,0,1]
	s_waitcnt vmcnt(3)
	v_lshlrev_b32_e32 v186, 16, v162
	v_and_b32_e32 v187, 0xffff0000, v162
	v_lshlrev_b32_e32 v188, 16, v163
	v_and_b32_e32 v189, 0xffff0000, v163
	v_pk_mul_f32 v[188:189], v[172:173], v[188:189]
	v_pk_mul_f32 v[186:187], v[170:171], v[186:187]
	v_pk_fma_f32 v[34:35], v[34:35], s[8:9], v[188:189] op_sel_hi:[1,0,1]
	v_pk_fma_f32 v[32:33], v[32:33], s[8:9], v[186:187] op_sel_hi:[1,0,1]
	s_waitcnt vmcnt(2)
	v_lshlrev_b32_e32 v186, 16, v164
	v_and_b32_e32 v187, 0xffff0000, v164
	v_lshlrev_b32_e32 v188, 16, v165
	v_and_b32_e32 v189, 0xffff0000, v165
	v_pk_mul_f32 v[188:189], v[176:177], v[188:189]
	v_pk_mul_f32 v[186:187], v[174:175], v[186:187]
	v_pk_fma_f32 v[30:31], v[30:31], s[8:9], v[188:189] op_sel_hi:[1,0,1]
	v_pk_fma_f32 v[28:29], v[28:29], s[8:9], v[186:187] op_sel_hi:[1,0,1]
	s_waitcnt vmcnt(1)
	v_lshlrev_b32_e32 v186, 16, v166
	v_and_b32_e32 v187, 0xffff0000, v166
	v_lshlrev_b32_e32 v188, 16, v167
	v_and_b32_e32 v189, 0xffff0000, v167
	v_pk_mul_f32 v[188:189], v[180:181], v[188:189]
	v_pk_mul_f32 v[186:187], v[178:179], v[186:187]
	v_pk_fma_f32 v[26:27], v[26:27], s[8:9], v[188:189] op_sel_hi:[1,0,1]
	v_pk_fma_f32 v[24:25], v[24:25], s[8:9], v[186:187] op_sel_hi:[1,0,1]
	s_waitcnt vmcnt(0)
	v_lshlrev_b32_e32 v186, 16, v168
	v_and_b32_e32 v187, 0xffff0000, v168
	v_lshlrev_b32_e32 v188, 16, v169
	v_and_b32_e32 v189, 0xffff0000, v169
	v_pk_mul_f32 v[188:189], v[184:185], v[188:189]
	v_pk_mul_f32 v[186:187], v[182:183], v[186:187]
	v_pk_fma_f32 v[22:23], v[22:23], s[8:9], v[188:189] op_sel_hi:[1,0,1]
	v_pk_fma_f32 v[20:21], v[20:21], s[8:9], v[186:187] op_sel_hi:[1,0,1]
.LBB0_119:
	s_and_b64 vcc, exec, s[38:39]
	s_cbranch_vccnz .LBB0_121
	global_load_dwordx4 v[138:141], v[8:9], off
	global_load_dwordx4 v[142:145], v[8:9], off offset:1024
	global_load_dwordx4 v[146:149], v[8:9], off offset:2048
	global_load_dwordx4 v[150:153], v[8:9], off offset:3072
	global_load_dwordx4 v[154:157], v[12:13], off
	global_load_dwordx4 v[158:161], v[12:13], off offset:1024
	global_load_dwordx4 v[162:165], v[12:13], off offset:2048
	global_load_dwordx4 v[166:169], v[12:13], off offset:3072
	s_waitcnt vmcnt(17)
	v_add_f32_e32 v89, v80, v81
	v_add_f32_e32 v91, v82, v83
	v_add_f32_e32 v89, v89, v91
	s_waitcnt vmcnt(16)
	v_add_f32_e32 v91, v76, v77
	v_add_f32_e32 v93, v78, v79
	v_add_f32_e32 v89, 0, v89
	v_add_f32_e32 v91, v91, v93
	v_add_f32_e32 v89, v91, v89
	s_waitcnt vmcnt(15)
	v_add_f32_e32 v91, v72, v73
	v_add_f32_e32 v93, v74, v75
	v_add_f32_e32 v91, v91, v93
	v_add_f32_e32 v89, v91, v89
	s_waitcnt vmcnt(14)
	v_add_f32_e32 v91, v68, v69
	v_add_f32_e32 v93, v70, v71
	v_add_f32_e32 v91, v91, v93
	v_add_f32_e32 v89, v91, v89
	v_lshl_add_u64 v[116:117], v[16:17], 0, v[116:117]
	s_nop 0
	v_add_f32_dpp v89, v89, v89 row_ror:8 row_mask:0xf bank_mask:0xf bound_ctrl:1
	s_nop 1
	v_add_f32_dpp v89, v89, v89 row_ror:4 row_mask:0xf bank_mask:0xf bound_ctrl:1
	s_nop 1
	v_add_f32_dpp v89, v89, v89 row_ror:2 row_mask:0xf bank_mask:0xf bound_ctrl:1
	s_nop 1
	v_add_f32_dpp v89, v89, v89 row_ror:1 row_mask:0xf bank_mask:0xf bound_ctrl:1
	v_mov_b32_e32 v91, v89
	s_nop 1
	v_permlane16_swap_b32_e32 v89, v91
	v_add_f32_e32 v89, v89, v91
	v_mov_b32_e32 v91, v89
	s_nop 1
	v_permlane32_swap_b32_e32 v89, v91
	v_add_f32_e32 v89, v89, v91
	v_fmamk_f32 v83, v89, 0xba800000, v83
	v_fmac_f32_e32 v81, 0xba800000, v89
	v_fmamk_f32 v82, v89, 0xba800000, v82
	v_fmamk_f32 v80, v89, 0xba800000, v80
	v_mul_f32_e32 v91, v81, v81
	v_mul_f32_e32 v93, v83, v83
	v_fmac_f32_e32 v91, v80, v80
	v_fmac_f32_e32 v93, v82, v82
	v_fmamk_f32 v79, v89, 0xba800000, v79
	v_fmac_f32_e32 v77, 0xba800000, v89
	v_add_f32_e32 v91, v91, v93
	v_fmamk_f32 v78, v89, 0xba800000, v78
	v_fmamk_f32 v76, v89, 0xba800000, v76
	v_mul_f32_e32 v93, v77, v77
	v_mul_f32_e32 v95, v79, v79
	v_fmac_f32_e32 v93, v76, v76
	v_fmac_f32_e32 v95, v78, v78
	v_add_f32_e32 v93, v93, v95
	v_fmamk_f32 v75, v89, 0xba800000, v75
	v_fmac_f32_e32 v73, 0xba800000, v89
	v_add_f32_e32 v91, v91, v93
	v_fmamk_f32 v74, v89, 0xba800000, v74
	v_fmamk_f32 v72, v89, 0xba800000, v72
	v_mul_f32_e32 v93, v73, v73
	v_mul_f32_e32 v95, v75, v75
	v_fmac_f32_e32 v93, v72, v72
	v_fmac_f32_e32 v95, v74, v74
	v_add_f32_e32 v93, v93, v95
	v_fmamk_f32 v71, v89, 0xba800000, v71
	v_fmac_f32_e32 v69, 0xba800000, v89
	v_add_f32_e32 v91, v93, v91
	v_fmamk_f32 v70, v89, 0xba800000, v70
	v_fmamk_f32 v68, v89, 0xba800000, v68
	v_mul_f32_e32 v89, v69, v69
	v_mul_f32_e32 v93, v71, v71
	v_fmac_f32_e32 v89, v68, v68
	v_fmac_f32_e32 v93, v70, v70
	v_add_f32_e32 v89, v89, v93
	v_add_f32_e32 v89, v89, v91
	s_nop 1
	v_add_f32_dpp v89, v89, v89 row_ror:8 row_mask:0xf bank_mask:0xf bound_ctrl:1
	s_nop 1
	v_add_f32_dpp v89, v89, v89 row_ror:4 row_mask:0xf bank_mask:0xf bound_ctrl:1
	s_nop 1
	v_add_f32_dpp v89, v89, v89 row_ror:2 row_mask:0xf bank_mask:0xf bound_ctrl:1
	s_nop 1
	v_add_f32_dpp v89, v89, v89 row_ror:1 row_mask:0xf bank_mask:0xf bound_ctrl:1
	v_mov_b32_e32 v91, v89
	s_nop 1
	v_permlane16_swap_b32_e32 v89, v91
	v_add_f32_e32 v89, v89, v91
	v_mov_b32_e32 v91, v89
	s_nop 1
	v_permlane32_swap_b32_e32 v89, v91
	v_add_f32_e32 v89, v89, v91
	v_fmamk_f32 v89, v89, 0x3a800000, v196
	v_cmp_gt_f32_e32 vcc, s22, v89
	v_mul_f32_e32 v91, 0x4b800000, v89
	s_nop 0
	v_cndmask_b32_e32 v89, v89, v91, vcc
	v_rsq_f32_e32 v89, v89
	s_nop 0
	v_mul_f32_e32 v91, 0x45800000, v89
	v_cndmask_b32_e32 v118, v89, v91, vcc
	v_pk_mul_f32 v[80:81], v[80:81], v[118:119] op_sel_hi:[1,0]
	v_pk_mul_f32 v[82:83], v[82:83], v[118:119] op_sel_hi:[1,0]
	s_waitcnt vmcnt(0)
	v_mov_b64_e32 v[120:121], v[138:139]
	v_mov_b64_e32 v[122:123], v[140:141]
	v_mov_b64_e32 v[124:125], v[154:155]
	v_mov_b64_e32 v[126:127], v[156:157]
	v_pk_fma_f32 v[80:81], v[120:121], v[80:81], v[124:125]
	v_pk_fma_f32 v[82:83], v[122:123], v[82:83], v[126:127]
	global_store_dwordx4 v[116:117], v[80:83], off nt
	v_pk_mul_f32 v[78:79], v[78:79], v[118:119] op_sel_hi:[1,0]
	v_pk_mul_f32 v[76:77], v[76:77], v[118:119] op_sel_hi:[1,0]
	v_pk_mul_f32 v[74:75], v[74:75], v[118:119] op_sel_hi:[1,0]
	v_pk_mul_f32 v[72:73], v[72:73], v[118:119] op_sel_hi:[1,0]
	v_pk_mul_f32 v[70:71], v[70:71], v[118:119] op_sel_hi:[1,0]
	v_pk_mul_f32 v[68:69], v[68:69], v[118:119] op_sel_hi:[1,0]
	s_nop 0
	v_mov_b64_e32 v[120:121], v[142:143]
	v_mov_b64_e32 v[122:123], v[144:145]
	v_mov_b64_e32 v[124:125], v[158:159]
	v_mov_b64_e32 v[126:127], v[160:161]
	v_pk_fma_f32 v[76:77], v[120:121], v[76:77], v[124:125]
	v_pk_fma_f32 v[78:79], v[122:123], v[78:79], v[126:127]
	global_store_dwordx4 v[116:117], v[76:79], off offset:1024 nt
	s_nop 0
	v_mov_b64_e32 v[120:121], v[146:147]
	v_mov_b64_e32 v[122:123], v[148:149]
	v_mov_b64_e32 v[124:125], v[162:163]
	v_mov_b64_e32 v[126:127], v[164:165]
	v_pk_fma_f32 v[72:73], v[120:121], v[72:73], v[124:125]
	v_pk_fma_f32 v[74:75], v[122:123], v[74:75], v[126:127]
	global_store_dwordx4 v[116:117], v[72:75], off offset:2048 nt
	s_nop 0
	v_mov_b64_e32 v[120:121], v[150:151]
	v_mov_b64_e32 v[122:123], v[152:153]
	v_mov_b64_e32 v[124:125], v[166:167]
	v_mov_b64_e32 v[126:127], v[168:169]
	v_pk_fma_f32 v[68:69], v[120:121], v[68:69], v[124:125]
	v_pk_fma_f32 v[70:71], v[122:123], v[70:71], v[126:127]
	global_store_dwordx4 v[116:117], v[68:71], off offset:3072 nt
.LBB0_121:
	s_waitcnt vmcnt(15)
	v_add_f32_e32 v89, v80, v81
	v_add_f32_e32 v91, v82, v83
	v_add_f32_e32 v89, v89, v91
	s_waitcnt vmcnt(14)
	v_add_f32_e32 v91, v76, v77
	v_add_f32_e32 v93, v78, v79
	v_add_f32_e32 v89, 0, v89
	v_add_f32_e32 v91, v91, v93
	v_add_f32_e32 v89, v91, v89
	s_waitcnt vmcnt(13)
	v_add_f32_e32 v91, v72, v73
	v_add_f32_e32 v93, v74, v75
	v_add_f32_e32 v91, v91, v93
	v_add_f32_e32 v89, v91, v89
	s_waitcnt vmcnt(12)
	v_add_f32_e32 v91, v68, v69
	v_add_f32_e32 v93, v70, v71
	v_add_f32_e32 v91, v91, v93
	v_add_f32_e32 v89, v91, v89
	v_lshrrev_b32_e32 v87, 20, v87
	v_add_u32_e32 v87, v86, v87
	v_add_f32_dpp v89, v89, v89 row_ror:8 row_mask:0xf bank_mask:0xf bound_ctrl:1
	v_ashrrev_i32_e32 v87, 12, v87
	s_mov_b64 s[8:9], 0x1000
	v_add_f32_dpp v89, v89, v89 row_ror:4 row_mask:0xf bank_mask:0xf bound_ctrl:1
	v_mov_b32_e32 v95, v2
	v_mov_b32_e32 v93, v2
	v_add_f32_dpp v89, v89, v89 row_ror:2 row_mask:0xf bank_mask:0xf bound_ctrl:1
	s_nop 1
	v_add_f32_dpp v89, v89, v89 row_ror:1 row_mask:0xf bank_mask:0xf bound_ctrl:1
	v_mov_b32_e32 v91, v89
	s_nop 1
	v_permlane16_swap_b32_e32 v89, v91
	v_add_f32_e32 v89, v89, v91
	v_mov_b32_e32 v91, v89
	s_nop 1
	v_permlane32_swap_b32_e32 v89, v91
	v_add_f32_e32 v89, v89, v91
	v_fmamk_f32 v117, v89, 0xba800000, v83
	v_fmac_f32_e32 v81, 0xba800000, v89
	v_fmamk_f32 v116, v89, 0xba800000, v82
	v_fmamk_f32 v80, v89, 0xba800000, v80
	v_mul_f32_e32 v82, v81, v81
	v_mul_f32_e32 v83, v117, v117
	v_fmac_f32_e32 v82, v80, v80
	v_fmac_f32_e32 v83, v116, v116
	v_add_f32_e32 v91, v82, v83
	v_fmamk_f32 v83, v89, 0xba800000, v79
	v_fmac_f32_e32 v77, 0xba800000, v89
	v_fmamk_f32 v82, v89, 0xba800000, v78
	v_fmamk_f32 v76, v89, 0xba800000, v76
	v_mul_f32_e32 v78, v77, v77
	v_mul_f32_e32 v79, v83, v83
	v_fmac_f32_e32 v78, v76, v76
	v_fmac_f32_e32 v79, v82, v82
	v_add_f32_e32 v78, v78, v79
	v_fmamk_f32 v79, v89, 0xba800000, v75
	v_fmac_f32_e32 v73, 0xba800000, v89
	v_add_f32_e32 v91, v91, v78
	v_fmamk_f32 v78, v89, 0xba800000, v74
	v_fmamk_f32 v72, v89, 0xba800000, v72
	v_mul_f32_e32 v74, v73, v73
	v_mul_f32_e32 v75, v79, v79
	v_fmac_f32_e32 v74, v72, v72
	v_fmac_f32_e32 v75, v78, v78
	v_fmamk_f32 v71, v89, 0xba800000, v71
	v_fmac_f32_e32 v69, 0xba800000, v89
	v_add_f32_e32 v74, v74, v75
	v_fmamk_f32 v70, v89, 0xba800000, v70
	v_fmamk_f32 v68, v89, 0xba800000, v68
	v_mul_f32_e32 v75, v69, v69
	v_mul_f32_e32 v89, v71, v71
	v_fmac_f32_e32 v75, v68, v68
	v_fmac_f32_e32 v89, v70, v70
	v_add_f32_e32 v74, v74, v91
	v_add_f32_e32 v75, v75, v89
	v_add_f32_e32 v74, v75, v74
	v_mov_b32_e32 v89, v2
	v_mov_b32_e32 v91, v2
	v_add_f32_dpp v74, v74, v74 row_ror:8 row_mask:0xf bank_mask:0xf bound_ctrl:1
	s_nop 1
	v_add_f32_dpp v74, v74, v74 row_ror:4 row_mask:0xf bank_mask:0xf bound_ctrl:1
	s_nop 1
	v_add_f32_dpp v74, v74, v74 row_ror:2 row_mask:0xf bank_mask:0xf bound_ctrl:1
	s_nop 1
	v_add_f32_dpp v74, v74, v74 row_ror:1 row_mask:0xf bank_mask:0xf bound_ctrl:1
	v_mov_b32_e32 v75, v74
	s_nop 1
	v_permlane16_swap_b32_e32 v74, v75
	v_add_f32_e32 v74, v74, v75
	v_mov_b32_e32 v75, v74
	s_nop 1
	v_permlane32_swap_b32_e32 v74, v75
	v_add_f32_e32 v74, v74, v75
	v_fmamk_f32 v74, v74, 0x3a800000, v196
	v_cmp_gt_f32_e32 vcc, s22, v74
	v_mul_f32_e32 v75, 0x4b800000, v74
	s_nop 0
	v_cndmask_b32_e32 v74, v74, v75, vcc
	v_rsq_f32_e32 v74, v74
	s_nop 0
	v_mul_f32_e32 v75, 0x45800000, v74
	v_cndmask_b32_e32 v74, v74, v75, vcc
	v_add_u32_e32 v75, s2, v87
	v_mul_hi_i32_i24_e32 v119, 0x3000, v75
	v_mul_i32_i24_e32 v118, 0x3000, v75
	v_lshl_add_u64 v[120:121], s[84:85], 0, v[118:119]
	v_lshl_add_u64 v[118:119], v[120:121], 0, s[8:9]
	v_lshl_add_u64 v[120:121], v[120:121], 0, v[94:95]
	v_lshl_add_u64 v[126:127], v[118:119], 0, v[94:95]
	v_pk_mul_f32 v[80:81], v[80:81], v[74:75] op_sel_hi:[1,0]
	v_pk_mul_f32 v[116:117], v[116:117], v[74:75] op_sel_hi:[1,0]
	v_pk_mul_f32 v[76:77], v[76:77], v[74:75] op_sel_hi:[1,0]
	v_pk_mul_f32 v[72:73], v[72:73], v[74:75] op_sel_hi:[1,0]
	v_pk_mul_f32 v[68:69], v[68:69], v[74:75] op_sel_hi:[1,0]
	v_pk_mul_f32 v[70:71], v[70:71], v[74:75] op_sel_hi:[1,0]
	s_and_b64 vcc, exec, s[38:39]
	s_nop 0
	v_mov_b64_e32 v[122:123], v[216:217]
	v_mov_b64_e32 v[124:125], v[218:219]
	v_mov_b64_e32 v[126:127], v[232:233]
	v_mov_b64_e32 v[128:129], v[234:235]
	v_pk_add_f32 v[128:129], v[128:129], 1.0 op_sel_hi:[1,0]
	v_pk_add_f32 v[126:127], v[126:127], 1.0 op_sel_hi:[1,0]
	v_pk_fma_f32 v[116:117], v[128:129], v[116:117], v[124:125]
	v_pk_fma_f32 v[80:81], v[126:127], v[80:81], v[122:123]
	v_lshl_add_u64 v[126:127], v[84:85], 0, v[114:115]
	v_cvt_pk_bf16_f32 v80, v80, v81
	v_cvt_pk_bf16_f32 v81, v116, v117
	global_store_dwordx2 v[126:127], v[80:81], off
	v_lshl_add_u64 v[80:81], v[118:119], 0, v[88:89]
	v_pk_mul_f32 v[80:81], v[82:83], v[74:75] op_sel_hi:[1,0]
	s_nop 0
	v_mov_b64_e32 v[114:115], v[220:221]
	v_mov_b64_e32 v[116:117], v[222:223]
	v_mov_b64_e32 v[122:123], v[236:237]
	v_mov_b64_e32 v[124:125], v[238:239]
	v_pk_add_f32 v[82:83], v[124:125], 1.0 op_sel_hi:[1,0]
	v_pk_add_f32 v[122:123], v[122:123], 1.0 op_sel_hi:[1,0]
	v_pk_fma_f32 v[80:81], v[82:83], v[80:81], v[116:117]
	v_pk_fma_f32 v[76:77], v[122:123], v[76:77], v[114:115]
	s_nop 0
	v_cvt_pk_bf16_f32 v76, v76, v77
	v_cvt_pk_bf16_f32 v77, v80, v81
	global_store_dwordx2 v[126:127], v[76:77], off offset:512
	v_lshl_add_u64 v[76:77], v[118:119], 0, v[90:91]
	v_pk_mul_f32 v[76:77], v[78:79], v[74:75] op_sel_hi:[1,0]
	s_nop 0
	v_mov_b64_e32 v[80:81], v[224:225]
	v_mov_b64_e32 v[82:83], v[226:227]
	v_mov_b64_e32 v[114:115], v[240:241]
	v_mov_b64_e32 v[116:117], v[242:243]
	v_pk_add_f32 v[78:79], v[116:117], 1.0 op_sel_hi:[1,0]
	v_pk_add_f32 v[114:115], v[114:115], 1.0 op_sel_hi:[1,0]
	v_pk_fma_f32 v[76:77], v[78:79], v[76:77], v[82:83]
	v_pk_fma_f32 v[72:73], v[114:115], v[72:73], v[80:81]
	s_nop 0
	v_cvt_pk_bf16_f32 v72, v72, v73
	v_cvt_pk_bf16_f32 v73, v76, v77
	global_store_dwordx2 v[126:127], v[72:73], off offset:1024
	v_lshl_add_u64 v[72:73], v[118:119], 0, v[92:93]
	s_nop 0
	v_mov_b64_e32 v[76:77], v[228:229]
	v_mov_b64_e32 v[78:79], v[230:231]
	v_mov_b64_e32 v[80:81], v[244:245]
	v_mov_b64_e32 v[82:83], v[246:247]
	v_pk_add_f32 v[72:73], v[82:83], 1.0 op_sel_hi:[1,0]
	v_pk_add_f32 v[74:75], v[80:81], 1.0 op_sel_hi:[1,0]
	v_pk_fma_f32 v[70:71], v[72:73], v[70:71], v[78:79]
	v_pk_fma_f32 v[68:69], v[74:75], v[68:69], v[76:77]
	s_nop 0
	v_cvt_pk_bf16_f32 v68, v68, v69
	v_cvt_pk_bf16_f32 v69, v70, v71
	global_store_dwordx2 v[126:127], v[68:69], off offset:1536
	s_cbranch_vccnz .LBB0_123
	v_add_f32_e32 v68, v64, v65
	v_add_f32_e32 v69, v66, v67
	v_add_f32_e32 v68, v68, v69
	v_add_f32_e32 v69, v60, v61
	v_add_f32_e32 v70, v62, v63
	v_add_f32_e32 v68, 0, v68
	v_add_f32_e32 v69, v69, v70
	v_add_f32_e32 v68, v69, v68
	v_add_f32_e32 v69, v56, v57
	v_add_f32_e32 v70, v58, v59
	v_add_f32_e32 v69, v69, v70
	v_add_f32_e32 v68, v69, v68
	v_add_f32_e32 v69, v52, v53
	v_add_f32_e32 v70, v54, v55
	v_add_f32_e32 v69, v69, v70
	v_add_f32_e32 v68, v69, v68
	v_lshl_add_u64 v[78:79], v[16:17], 0, v[112:113]
	s_nop 0
	v_add_f32_dpp v68, v68, v68 row_ror:8 row_mask:0xf bank_mask:0xf bound_ctrl:1
	s_nop 1
	v_add_f32_dpp v68, v68, v68 row_ror:4 row_mask:0xf bank_mask:0xf bound_ctrl:1
	s_nop 1
	v_add_f32_dpp v68, v68, v68 row_ror:2 row_mask:0xf bank_mask:0xf bound_ctrl:1
	s_nop 1
	v_add_f32_dpp v68, v68, v68 row_ror:1 row_mask:0xf bank_mask:0xf bound_ctrl:1
	v_mov_b32_e32 v69, v68
	s_nop 1
	v_permlane16_swap_b32_e32 v68, v69
	v_add_f32_e32 v68, v68, v69
	v_mov_b32_e32 v69, v68
	s_nop 1
	v_permlane32_swap_b32_e32 v68, v69
	v_add_f32_e32 v68, v68, v69
	v_fmamk_f32 v67, v68, 0xba800000, v67
	v_fmac_f32_e32 v65, 0xba800000, v68
	v_fmamk_f32 v66, v68, 0xba800000, v66
	v_fmamk_f32 v64, v68, 0xba800000, v64
	v_mul_f32_e32 v69, v65, v65
	v_mul_f32_e32 v70, v67, v67
	v_fmac_f32_e32 v69, v64, v64
	v_fmac_f32_e32 v70, v66, v66
	v_fmamk_f32 v63, v68, 0xba800000, v63
	v_fmac_f32_e32 v61, 0xba800000, v68
	v_add_f32_e32 v69, v69, v70
	v_fmamk_f32 v62, v68, 0xba800000, v62
	v_fmamk_f32 v60, v68, 0xba800000, v60
	v_mul_f32_e32 v70, v61, v61
	v_mul_f32_e32 v71, v63, v63
	v_fmac_f32_e32 v70, v60, v60
	v_fmac_f32_e32 v71, v62, v62
	v_add_f32_e32 v70, v70, v71
	v_fmamk_f32 v59, v68, 0xba800000, v59
	v_fmac_f32_e32 v57, 0xba800000, v68
	v_add_f32_e32 v69, v69, v70
	v_fmamk_f32 v58, v68, 0xba800000, v58
	v_fmamk_f32 v56, v68, 0xba800000, v56
	v_mul_f32_e32 v70, v57, v57
	v_mul_f32_e32 v71, v59, v59
	v_fmac_f32_e32 v70, v56, v56
	v_fmac_f32_e32 v71, v58, v58
	v_add_f32_e32 v70, v70, v71
	v_fmamk_f32 v55, v68, 0xba800000, v55
	v_fmac_f32_e32 v53, 0xba800000, v68
	v_add_f32_e32 v69, v70, v69
	v_fmamk_f32 v54, v68, 0xba800000, v54
	v_fmamk_f32 v52, v68, 0xba800000, v52
	v_mul_f32_e32 v68, v53, v53
	v_mul_f32_e32 v70, v55, v55
	v_fmac_f32_e32 v68, v52, v52
	v_fmac_f32_e32 v70, v54, v54
	v_add_f32_e32 v68, v68, v70
	v_add_f32_e32 v68, v68, v69
	s_nop 1
	v_add_f32_dpp v68, v68, v68 row_ror:8 row_mask:0xf bank_mask:0xf bound_ctrl:1
	s_nop 1
	v_add_f32_dpp v68, v68, v68 row_ror:4 row_mask:0xf bank_mask:0xf bound_ctrl:1
	s_nop 1
	v_add_f32_dpp v68, v68, v68 row_ror:2 row_mask:0xf bank_mask:0xf bound_ctrl:1
	s_nop 1
	v_add_f32_dpp v68, v68, v68 row_ror:1 row_mask:0xf bank_mask:0xf bound_ctrl:1
	v_mov_b32_e32 v69, v68
	s_nop 1
	v_permlane16_swap_b32_e32 v68, v69
	v_add_f32_e32 v68, v68, v69
	v_mov_b32_e32 v69, v68
	s_nop 1
	v_permlane32_swap_b32_e32 v68, v69
	v_add_f32_e32 v68, v68, v69
	v_fmamk_f32 v68, v68, 0x3a800000, v196
	v_cmp_gt_f32_e32 vcc, s22, v68
	v_mul_f32_e32 v69, 0x4b800000, v68
	s_nop 0
	v_cndmask_b32_e32 v68, v68, v69, vcc
	v_rsq_f32_e32 v68, v68
	s_nop 0
	v_mul_f32_e32 v69, 0x45800000, v68
	v_cndmask_b32_e32 v68, v68, v69, vcc
	v_pk_mul_f32 v[64:65], v[64:65], v[68:69] op_sel_hi:[1,0]
	v_pk_mul_f32 v[66:67], v[66:67], v[68:69] op_sel_hi:[1,0]
	v_pk_mul_f32 v[62:63], v[62:63], v[68:69] op_sel_hi:[1,0]
	v_pk_mul_f32 v[60:61], v[60:61], v[68:69] op_sel_hi:[1,0]
	v_pk_mul_f32 v[58:59], v[58:59], v[68:69] op_sel_hi:[1,0]
	v_pk_mul_f32 v[56:57], v[56:57], v[68:69] op_sel_hi:[1,0]
	v_pk_mul_f32 v[54:55], v[54:55], v[68:69] op_sel_hi:[1,0]
	v_pk_mul_f32 v[52:53], v[52:53], v[68:69] op_sel_hi:[1,0]
	s_nop 0
	v_mov_b64_e32 v[70:71], v[138:139]
	v_mov_b64_e32 v[72:73], v[140:141]
	v_mov_b64_e32 v[74:75], v[154:155]
	v_mov_b64_e32 v[76:77], v[156:157]
	v_pk_fma_f32 v[66:67], v[72:73], v[66:67], v[76:77]
	v_pk_fma_f32 v[64:65], v[70:71], v[64:65], v[74:75]
	global_store_dwordx4 v[78:79], v[64:67], off nt
	s_nop 0
	v_mov_b64_e32 v[70:71], v[142:143]
	v_mov_b64_e32 v[72:73], v[144:145]
	v_mov_b64_e32 v[74:75], v[158:159]
	v_mov_b64_e32 v[76:77], v[160:161]
	v_pk_fma_f32 v[60:61], v[70:71], v[60:61], v[74:75]
	v_pk_fma_f32 v[62:63], v[72:73], v[62:63], v[76:77]
	global_store_dwordx4 v[78:79], v[60:63], off offset:1024 nt
	s_nop 0
	v_mov_b64_e32 v[70:71], v[146:147]
	v_mov_b64_e32 v[72:73], v[148:149]
	v_mov_b64_e32 v[74:75], v[162:163]
	v_mov_b64_e32 v[76:77], v[164:165]
	v_pk_fma_f32 v[56:57], v[70:71], v[56:57], v[74:75]
	v_pk_fma_f32 v[58:59], v[72:73], v[58:59], v[76:77]
	global_store_dwordx4 v[78:79], v[56:59], off offset:2048 nt
	s_nop 0
	v_mov_b64_e32 v[70:71], v[150:151]
	v_mov_b64_e32 v[72:73], v[152:153]
	v_mov_b64_e32 v[74:75], v[166:167]
	v_mov_b64_e32 v[76:77], v[168:169]
	v_pk_fma_f32 v[52:53], v[70:71], v[52:53], v[74:75]
	v_pk_fma_f32 v[54:55], v[72:73], v[54:55], v[76:77]
	global_store_dwordx4 v[78:79], v[52:55], off offset:3072 nt
.LBB0_123:
	s_waitcnt vmcnt(12)
	v_add_f32_e32 v68, v64, v65
	v_add_f32_e32 v69, v66, v67
	v_add_f32_e32 v68, v68, v69
	v_add_f32_e32 v69, v60, v61
	v_add_f32_e32 v70, v62, v63
	v_add_f32_e32 v68, 0, v68
	v_add_f32_e32 v69, v69, v70
	v_add_f32_e32 v68, v69, v68
	v_add_f32_e32 v69, v56, v57
	v_add_f32_e32 v70, v58, v59
	v_add_f32_e32 v69, v69, v70
	v_add_f32_e32 v68, v69, v68
	v_add_f32_e32 v69, v52, v53
	v_add_f32_e32 v70, v54, v55
	v_add_f32_e32 v69, v69, v70
	v_add_f32_e32 v68, v69, v68
	v_lshrrev_b32_e32 v19, 20, v19
	v_add_u32_e32 v19, v110, v19
	v_add_f32_dpp v68, v68, v68 row_ror:8 row_mask:0xf bank_mask:0xf bound_ctrl:1
	v_ashrrev_i32_e32 v19, 12, v19
	v_add_u32_e32 v19, s2, v19
	v_add_f32_dpp v68, v68, v68 row_ror:4 row_mask:0xf bank_mask:0xf bound_ctrl:1
	s_nop 1
	v_add_f32_dpp v68, v68, v68 row_ror:2 row_mask:0xf bank_mask:0xf bound_ctrl:1
	s_nop 1
	v_add_f32_dpp v68, v68, v68 row_ror:1 row_mask:0xf bank_mask:0xf bound_ctrl:1
	v_mov_b32_e32 v69, v68
	s_nop 1
	v_permlane16_swap_b32_e32 v68, v69
	v_add_f32_e32 v68, v68, v69
	v_mov_b32_e32 v69, v68
	s_nop 1
	v_permlane32_swap_b32_e32 v68, v69
	v_add_f32_e32 v70, v68, v69
	v_fmamk_f32 v69, v70, 0xba800000, v67
	v_fmac_f32_e32 v65, 0xba800000, v70
	v_fmamk_f32 v68, v70, 0xba800000, v66
	v_fmamk_f32 v64, v70, 0xba800000, v64
	v_mul_f32_e32 v66, v65, v65
	v_mul_f32_e32 v67, v69, v69
	v_fmac_f32_e32 v66, v64, v64
	v_fmac_f32_e32 v67, v68, v68
	v_add_f32_e32 v71, v66, v67
	v_fmamk_f32 v67, v70, 0xba800000, v63
	v_fmac_f32_e32 v61, 0xba800000, v70
	v_fmamk_f32 v66, v70, 0xba800000, v62
	v_fmamk_f32 v60, v70, 0xba800000, v60
	v_mul_f32_e32 v62, v61, v61
	v_mul_f32_e32 v63, v67, v67
	v_fmac_f32_e32 v62, v60, v60
	v_fmac_f32_e32 v63, v66, v66
	v_add_f32_e32 v62, v62, v63
	v_fmamk_f32 v63, v70, 0xba800000, v59
	v_fmac_f32_e32 v57, 0xba800000, v70
	v_add_f32_e32 v71, v71, v62
	v_fmamk_f32 v62, v70, 0xba800000, v58
	v_fmamk_f32 v56, v70, 0xba800000, v56
	v_mul_f32_e32 v58, v57, v57
	v_mul_f32_e32 v59, v63, v63
	v_fmac_f32_e32 v58, v56, v56
	v_fmac_f32_e32 v59, v62, v62
	v_fmamk_f32 v55, v70, 0xba800000, v55
	v_fmac_f32_e32 v53, 0xba800000, v70
	v_add_f32_e32 v58, v58, v59
	v_fmamk_f32 v54, v70, 0xba800000, v54
	v_fmamk_f32 v52, v70, 0xba800000, v52
	v_mul_f32_e32 v59, v53, v53
	v_mul_f32_e32 v70, v55, v55
	v_fmac_f32_e32 v59, v52, v52
	v_fmac_f32_e32 v70, v54, v54
	v_add_f32_e32 v58, v58, v71
	v_add_f32_e32 v59, v59, v70
	v_mul_hi_i32_i24_e32 v71, 0x3000, v19
	v_mul_i32_i24_e32 v70, 0x3000, v19
	v_lshl_add_u64 v[72:73], s[84:85], 0, v[70:71]
	v_lshl_add_u64 v[70:71], v[72:73], 0, s[8:9]
	v_lshl_add_u64 v[72:73], v[72:73], 0, v[94:95]
	v_lshl_add_u64 v[78:79], v[70:71], 0, v[94:95]
	v_add_f32_e32 v58, v59, v58
	s_nop 0
	v_mov_b64_e32 v[74:75], v[216:217]
	v_mov_b64_e32 v[76:77], v[218:219]
	v_mov_b64_e32 v[78:79], v[232:233]
	v_mov_b64_e32 v[80:81], v[234:235]
	v_pk_add_f32 v[80:81], v[80:81], 1.0 op_sel_hi:[1,0]
	v_add_f32_dpp v58, v58, v58 row_ror:8 row_mask:0xf bank_mask:0xf bound_ctrl:1
	v_pk_add_f32 v[78:79], v[78:79], 1.0 op_sel_hi:[1,0]
	s_nop 0
	v_add_f32_dpp v58, v58, v58 row_ror:4 row_mask:0xf bank_mask:0xf bound_ctrl:1
	s_nop 1
	v_add_f32_dpp v58, v58, v58 row_ror:2 row_mask:0xf bank_mask:0xf bound_ctrl:1
	s_nop 1
	v_add_f32_dpp v58, v58, v58 row_ror:1 row_mask:0xf bank_mask:0xf bound_ctrl:1
	v_mov_b32_e32 v59, v58
	s_nop 1
	v_permlane16_swap_b32_e32 v58, v59
	v_add_f32_e32 v58, v58, v59
	v_mov_b32_e32 v59, v58
	s_nop 1
	v_permlane32_swap_b32_e32 v58, v59
	v_add_f32_e32 v58, v58, v59
	v_fmamk_f32 v58, v58, 0x3a800000, v196
	v_cmp_gt_f32_e32 vcc, s22, v58
	v_mul_f32_e32 v59, 0x4b800000, v58
	s_nop 0
	v_cndmask_b32_e32 v58, v58, v59, vcc
	v_rsq_f32_e32 v58, v58
	s_nop 0
	v_mul_f32_e32 v59, 0x45800000, v58
	v_cndmask_b32_e32 v58, v58, v59, vcc
	v_pk_mul_f32 v[64:65], v[64:65], v[58:59] op_sel_hi:[1,0]
	v_pk_mul_f32 v[68:69], v[68:69], v[58:59] op_sel_hi:[1,0]
	v_pk_fma_f32 v[64:65], v[78:79], v[64:65], v[74:75]
	v_pk_fma_f32 v[68:69], v[80:81], v[68:69], v[76:77]
	v_cvt_pk_bf16_f32 v64, v64, v65
	v_cvt_pk_bf16_f32 v65, v68, v69
	v_lshl_add_u64 v[68:69], v[84:85], 0, v[108:109]
	global_store_dwordx2 v[68:69], v[64:65], off
	v_lshl_add_u64 v[64:65], v[70:71], 0, v[88:89]
	v_pk_mul_f32 v[60:61], v[60:61], v[58:59] op_sel_hi:[1,0]
	v_pk_mul_f32 v[64:65], v[66:67], v[58:59] op_sel_hi:[1,0]
	v_pk_mul_f32 v[56:57], v[56:57], v[58:59] op_sel_hi:[1,0]
	v_pk_mul_f32 v[52:53], v[52:53], v[58:59] op_sel_hi:[1,0]
	v_pk_mul_f32 v[54:55], v[54:55], v[58:59] op_sel_hi:[1,0]
	s_and_b64 vcc, exec, s[38:39]
	s_nop 0
	v_mov_b64_e32 v[74:75], v[220:221]
	v_mov_b64_e32 v[76:77], v[222:223]
	v_mov_b64_e32 v[78:79], v[236:237]
	v_mov_b64_e32 v[80:81], v[238:239]
	v_pk_add_f32 v[66:67], v[80:81], 1.0 op_sel_hi:[1,0]
	v_pk_add_f32 v[78:79], v[78:79], 1.0 op_sel_hi:[1,0]
	v_pk_fma_f32 v[64:65], v[66:67], v[64:65], v[76:77]
	v_pk_fma_f32 v[60:61], v[78:79], v[60:61], v[74:75]
	s_nop 0
	v_cvt_pk_bf16_f32 v60, v60, v61
	v_cvt_pk_bf16_f32 v61, v64, v65
	global_store_dwordx2 v[68:69], v[60:61], off offset:512
	v_lshl_add_u64 v[60:61], v[70:71], 0, v[90:91]
	v_pk_mul_f32 v[60:61], v[62:63], v[58:59] op_sel_hi:[1,0]
	s_nop 0
	v_mov_b64_e32 v[64:65], v[224:225]
	v_mov_b64_e32 v[66:67], v[226:227]
	v_mov_b64_e32 v[74:75], v[240:241]
	v_mov_b64_e32 v[76:77], v[242:243]
	v_pk_add_f32 v[62:63], v[76:77], 1.0 op_sel_hi:[1,0]
	v_pk_add_f32 v[74:75], v[74:75], 1.0 op_sel_hi:[1,0]
	v_pk_fma_f32 v[60:61], v[62:63], v[60:61], v[66:67]
	v_pk_fma_f32 v[56:57], v[74:75], v[56:57], v[64:65]
	s_nop 0
	v_cvt_pk_bf16_f32 v56, v56, v57
	v_cvt_pk_bf16_f32 v57, v60, v61
	global_store_dwordx2 v[68:69], v[56:57], off offset:1024
	v_lshl_add_u64 v[56:57], v[70:71], 0, v[92:93]
	s_nop 0
	v_mov_b64_e32 v[60:61], v[228:229]
	v_mov_b64_e32 v[62:63], v[230:231]
	v_mov_b64_e32 v[64:65], v[244:245]
	v_mov_b64_e32 v[66:67], v[246:247]
	v_pk_add_f32 v[56:57], v[66:67], 1.0 op_sel_hi:[1,0]
	v_pk_add_f32 v[58:59], v[64:65], 1.0 op_sel_hi:[1,0]
	v_pk_fma_f32 v[54:55], v[56:57], v[54:55], v[62:63]
	v_pk_fma_f32 v[52:53], v[58:59], v[52:53], v[60:61]
	s_nop 0
	v_cvt_pk_bf16_f32 v52, v52, v53
	v_cvt_pk_bf16_f32 v53, v54, v55
	global_store_dwordx2 v[68:69], v[52:53], off offset:1536
	s_cbranch_vccnz .LBB0_125
	v_add_f32_e32 v19, v48, v49
	v_add_f32_e32 v52, v50, v51
	v_add_f32_e32 v19, v19, v52
	v_add_f32_e32 v52, v44, v45
	v_add_f32_e32 v53, v46, v47
	v_add_f32_e32 v19, 0, v19
	v_add_f32_e32 v52, v52, v53
	v_add_f32_e32 v19, v52, v19
	v_add_f32_e32 v52, v40, v41
	v_add_f32_e32 v53, v42, v43
	v_add_f32_e32 v52, v52, v53
	v_add_f32_e32 v19, v52, v19
	v_add_f32_e32 v52, v36, v37
	v_add_f32_e32 v53, v38, v39
	v_add_f32_e32 v52, v52, v53
	v_add_f32_e32 v19, v52, v19
	v_lshl_add_u64 v[62:63], v[16:17], 0, v[106:107]
	s_nop 0
	v_add_f32_dpp v19, v19, v19 row_ror:8 row_mask:0xf bank_mask:0xf bound_ctrl:1
	s_nop 1
	v_add_f32_dpp v19, v19, v19 row_ror:4 row_mask:0xf bank_mask:0xf bound_ctrl:1
	s_nop 1
	v_add_f32_dpp v19, v19, v19 row_ror:2 row_mask:0xf bank_mask:0xf bound_ctrl:1
	s_nop 1
	v_add_f32_dpp v19, v19, v19 row_ror:1 row_mask:0xf bank_mask:0xf bound_ctrl:1
	v_mov_b32_e32 v52, v19
	s_nop 1
	v_permlane16_swap_b32_e32 v19, v52
	v_add_f32_e32 v19, v19, v52
	v_mov_b32_e32 v52, v19
	s_nop 1
	v_permlane32_swap_b32_e32 v19, v52
	v_add_f32_e32 v19, v19, v52
	v_fmamk_f32 v51, v19, 0xba800000, v51
	v_fmac_f32_e32 v49, 0xba800000, v19
	v_fmamk_f32 v50, v19, 0xba800000, v50
	v_fmamk_f32 v48, v19, 0xba800000, v48
	v_mul_f32_e32 v52, v49, v49
	v_mul_f32_e32 v53, v51, v51
	v_fmac_f32_e32 v52, v48, v48
	v_fmac_f32_e32 v53, v50, v50
	v_fmamk_f32 v47, v19, 0xba800000, v47
	v_fmac_f32_e32 v45, 0xba800000, v19
	v_add_f32_e32 v52, v52, v53
	v_fmamk_f32 v46, v19, 0xba800000, v46
	v_fmamk_f32 v44, v19, 0xba800000, v44
	v_mul_f32_e32 v53, v45, v45
	v_mul_f32_e32 v54, v47, v47
	v_fmac_f32_e32 v53, v44, v44
	v_fmac_f32_e32 v54, v46, v46
	v_add_f32_e32 v53, v53, v54
	v_fmamk_f32 v43, v19, 0xba800000, v43
	v_fmac_f32_e32 v41, 0xba800000, v19
	v_add_f32_e32 v52, v52, v53
	v_fmamk_f32 v42, v19, 0xba800000, v42
	v_fmamk_f32 v40, v19, 0xba800000, v40
	v_mul_f32_e32 v53, v41, v41
	v_mul_f32_e32 v54, v43, v43
	v_fmac_f32_e32 v53, v40, v40
	v_fmac_f32_e32 v54, v42, v42
	v_add_f32_e32 v53, v53, v54
	v_fmamk_f32 v39, v19, 0xba800000, v39
	v_fmac_f32_e32 v37, 0xba800000, v19
	v_add_f32_e32 v52, v53, v52
	v_fmamk_f32 v38, v19, 0xba800000, v38
	v_fmamk_f32 v36, v19, 0xba800000, v36
	v_mul_f32_e32 v19, v37, v37
	v_mul_f32_e32 v53, v39, v39
	v_fmac_f32_e32 v19, v36, v36
	v_fmac_f32_e32 v53, v38, v38
	v_add_f32_e32 v19, v19, v53
	v_add_f32_e32 v19, v19, v52
	s_nop 1
	v_add_f32_dpp v19, v19, v19 row_ror:8 row_mask:0xf bank_mask:0xf bound_ctrl:1
	s_nop 1
	v_add_f32_dpp v19, v19, v19 row_ror:4 row_mask:0xf bank_mask:0xf bound_ctrl:1
	s_nop 1
	v_add_f32_dpp v19, v19, v19 row_ror:2 row_mask:0xf bank_mask:0xf bound_ctrl:1
	s_nop 1
	v_add_f32_dpp v19, v19, v19 row_ror:1 row_mask:0xf bank_mask:0xf bound_ctrl:1
	v_mov_b32_e32 v52, v19
	s_nop 1
	v_permlane16_swap_b32_e32 v19, v52
	v_add_f32_e32 v19, v19, v52
	v_mov_b32_e32 v52, v19
	s_nop 1
	v_permlane32_swap_b32_e32 v19, v52
	v_add_f32_e32 v19, v19, v52
	v_fmamk_f32 v19, v19, 0x3a800000, v196
	v_cmp_gt_f32_e32 vcc, s22, v19
	v_mul_f32_e32 v52, 0x4b800000, v19
	s_nop 0
	v_cndmask_b32_e32 v19, v19, v52, vcc
	v_rsq_f32_e32 v19, v19
	s_nop 0
	v_mul_f32_e32 v52, 0x45800000, v19
	v_cndmask_b32_e32 v52, v19, v52, vcc
	v_pk_mul_f32 v[48:49], v[48:49], v[52:53] op_sel_hi:[1,0]
	v_pk_mul_f32 v[50:51], v[50:51], v[52:53] op_sel_hi:[1,0]
	v_pk_mul_f32 v[46:47], v[46:47], v[52:53] op_sel_hi:[1,0]
	v_pk_mul_f32 v[44:45], v[44:45], v[52:53] op_sel_hi:[1,0]
	v_pk_mul_f32 v[42:43], v[42:43], v[52:53] op_sel_hi:[1,0]
	v_pk_mul_f32 v[40:41], v[40:41], v[52:53] op_sel_hi:[1,0]
	v_pk_mul_f32 v[38:39], v[38:39], v[52:53] op_sel_hi:[1,0]
	v_pk_mul_f32 v[36:37], v[36:37], v[52:53] op_sel_hi:[1,0]
	s_nop 0
	v_mov_b64_e32 v[54:55], v[138:139]
	v_mov_b64_e32 v[56:57], v[140:141]
	v_mov_b64_e32 v[58:59], v[154:155]
	v_mov_b64_e32 v[60:61], v[156:157]
	v_pk_fma_f32 v[50:51], v[56:57], v[50:51], v[60:61]
	v_pk_fma_f32 v[48:49], v[54:55], v[48:49], v[58:59]
	global_store_dwordx4 v[62:63], v[48:51], off nt
	s_nop 0
	v_mov_b64_e32 v[54:55], v[142:143]
	v_mov_b64_e32 v[56:57], v[144:145]
	v_mov_b64_e32 v[58:59], v[158:159]
	v_mov_b64_e32 v[60:61], v[160:161]
	v_pk_fma_f32 v[44:45], v[54:55], v[44:45], v[58:59]
	v_pk_fma_f32 v[46:47], v[56:57], v[46:47], v[60:61]
	global_store_dwordx4 v[62:63], v[44:47], off offset:1024 nt
	s_nop 0
	v_mov_b64_e32 v[54:55], v[146:147]
	v_mov_b64_e32 v[56:57], v[148:149]
	v_mov_b64_e32 v[58:59], v[162:163]
	v_mov_b64_e32 v[60:61], v[164:165]
	v_pk_fma_f32 v[40:41], v[54:55], v[40:41], v[58:59]
	v_pk_fma_f32 v[42:43], v[56:57], v[42:43], v[60:61]
	global_store_dwordx4 v[62:63], v[40:43], off offset:2048 nt
	s_nop 0
	v_mov_b64_e32 v[54:55], v[150:151]
	v_mov_b64_e32 v[56:57], v[152:153]
	v_mov_b64_e32 v[58:59], v[166:167]
	v_mov_b64_e32 v[60:61], v[168:169]
	v_pk_fma_f32 v[36:37], v[54:55], v[36:37], v[58:59]
	v_pk_fma_f32 v[38:39], v[56:57], v[38:39], v[60:61]
	global_store_dwordx4 v[62:63], v[36:39], off offset:3072 nt
.LBB0_125:
	s_waitcnt vmcnt(12)
	v_add_f32_e32 v19, v48, v49
	v_add_f32_e32 v52, v50, v51
	v_add_f32_e32 v19, v19, v52
	v_add_f32_e32 v52, v44, v45
	v_add_f32_e32 v53, v46, v47
	v_add_f32_e32 v19, 0, v19
	v_add_f32_e32 v52, v52, v53
	v_add_f32_e32 v19, v52, v19
	v_add_f32_e32 v52, v40, v41
	v_add_f32_e32 v53, v42, v43
	v_add_f32_e32 v52, v52, v53
	v_add_f32_e32 v19, v52, v19
	v_add_f32_e32 v52, v36, v37
	v_add_f32_e32 v53, v38, v39
	v_add_f32_e32 v52, v52, v53
	v_add_f32_e32 v19, v52, v19
	v_lshrrev_b32_e32 v15, 20, v15
	v_add_u32_e32 v15, v104, v15
	v_add_f32_dpp v19, v19, v19 row_ror:8 row_mask:0xf bank_mask:0xf bound_ctrl:1
	v_ashrrev_i32_e32 v15, 12, v15
	v_add_u32_e32 v15, s2, v15
	v_add_f32_dpp v19, v19, v19 row_ror:4 row_mask:0xf bank_mask:0xf bound_ctrl:1
	v_mul_hi_i32_i24_e32 v55, 0x3000, v15
	v_mov_b32_e32 v95, v2
	v_add_f32_dpp v19, v19, v19 row_ror:2 row_mask:0xf bank_mask:0xf bound_ctrl:1
	v_mov_b32_e32 v89, v2
	v_mov_b32_e32 v91, v2
	v_add_f32_dpp v19, v19, v19 row_ror:1 row_mask:0xf bank_mask:0xf bound_ctrl:1
	v_mov_b32_e32 v52, v19
	s_nop 1
	v_permlane16_swap_b32_e32 v19, v52
	v_add_f32_e32 v19, v19, v52
	v_mov_b32_e32 v52, v19
	s_nop 1
	v_permlane32_swap_b32_e32 v19, v52
	v_add_f32_e32 v19, v19, v52
	v_fmamk_f32 v53, v19, 0xba800000, v51
	v_fmac_f32_e32 v49, 0xba800000, v19
	v_fmamk_f32 v52, v19, 0xba800000, v50
	v_fmamk_f32 v48, v19, 0xba800000, v48
	v_mul_f32_e32 v50, v49, v49
	v_mul_f32_e32 v51, v53, v53
	v_fmac_f32_e32 v50, v48, v48
	v_fmac_f32_e32 v51, v52, v52
	v_add_f32_e32 v54, v50, v51
	v_fmamk_f32 v51, v19, 0xba800000, v47
	v_fmac_f32_e32 v45, 0xba800000, v19
	v_fmamk_f32 v50, v19, 0xba800000, v46
	v_fmamk_f32 v44, v19, 0xba800000, v44
	v_mul_f32_e32 v46, v45, v45
	v_mul_f32_e32 v47, v51, v51
	v_fmac_f32_e32 v46, v44, v44
	v_fmac_f32_e32 v47, v50, v50
	v_add_f32_e32 v46, v46, v47
	v_fmamk_f32 v47, v19, 0xba800000, v43
	v_fmac_f32_e32 v41, 0xba800000, v19
	v_add_f32_e32 v54, v54, v46
	v_fmamk_f32 v46, v19, 0xba800000, v42
	v_fmamk_f32 v40, v19, 0xba800000, v40
	v_mul_f32_e32 v42, v41, v41
	v_mul_f32_e32 v43, v47, v47
	v_fmac_f32_e32 v42, v40, v40
	v_fmac_f32_e32 v43, v46, v46
	v_add_f32_e32 v42, v42, v43
	v_add_f32_e32 v42, v42, v54
	v_mul_i32_i24_e32 v54, 0x3000, v15
	v_lshl_add_u64 v[56:57], s[84:85], 0, v[54:55]
	v_lshl_add_u64 v[54:55], v[56:57], 0, s[8:9]
	v_lshl_add_u64 v[56:57], v[56:57], 0, v[94:95]
	v_lshl_add_u64 v[62:63], v[54:55], 0, v[94:95]
	v_fmamk_f32 v39, v19, 0xba800000, v39
	v_fmac_f32_e32 v37, 0xba800000, v19
	v_fmamk_f32 v38, v19, 0xba800000, v38
	v_fmamk_f32 v36, v19, 0xba800000, v36
	v_mul_f32_e32 v19, v37, v37
	v_mul_f32_e32 v43, v39, v39
	v_fmac_f32_e32 v19, v36, v36
	v_fmac_f32_e32 v43, v38, v38
	v_add_f32_e32 v19, v19, v43
	v_add_f32_e32 v19, v19, v42
	v_mov_b32_e32 v93, v2
	s_nop 0
	v_mov_b64_e32 v[58:59], v[216:217]
	v_mov_b64_e32 v[60:61], v[218:219]
	v_mov_b64_e32 v[62:63], v[232:233]
	v_mov_b64_e32 v[64:65], v[234:235]
	v_pk_add_f32 v[64:65], v[64:65], 1.0 op_sel_hi:[1,0]
	v_add_f32_dpp v19, v19, v19 row_ror:8 row_mask:0xf bank_mask:0xf bound_ctrl:1
	v_pk_add_f32 v[62:63], v[62:63], 1.0 op_sel_hi:[1,0]
	s_nop 0
	v_add_f32_dpp v19, v19, v19 row_ror:4 row_mask:0xf bank_mask:0xf bound_ctrl:1
	s_nop 1
	v_add_f32_dpp v19, v19, v19 row_ror:2 row_mask:0xf bank_mask:0xf bound_ctrl:1
	s_nop 1
	v_add_f32_dpp v19, v19, v19 row_ror:1 row_mask:0xf bank_mask:0xf bound_ctrl:1
	v_mov_b32_e32 v42, v19
	s_nop 1
	v_permlane16_swap_b32_e32 v19, v42
	v_add_f32_e32 v19, v19, v42
	v_mov_b32_e32 v42, v19
	s_nop 1
	v_permlane32_swap_b32_e32 v19, v42
	v_add_f32_e32 v19, v19, v42
	v_fmamk_f32 v19, v19, 0x3a800000, v196
	v_cmp_gt_f32_e32 vcc, s22, v19
	v_mul_f32_e32 v42, 0x4b800000, v19
	s_nop 0
	v_cndmask_b32_e32 v19, v19, v42, vcc
	v_rsq_f32_e32 v19, v19
	s_nop 0
	v_mul_f32_e32 v42, 0x45800000, v19
	v_cndmask_b32_e32 v42, v19, v42, vcc
	v_pk_mul_f32 v[48:49], v[48:49], v[42:43] op_sel_hi:[1,0]
	v_pk_mul_f32 v[52:53], v[52:53], v[42:43] op_sel_hi:[1,0]
	v_pk_fma_f32 v[48:49], v[62:63], v[48:49], v[58:59]
	v_pk_fma_f32 v[52:53], v[64:65], v[52:53], v[60:61]
	v_cvt_pk_bf16_f32 v48, v48, v49
	v_cvt_pk_bf16_f32 v49, v52, v53
	v_lshl_add_u64 v[52:53], v[84:85], 0, v[102:103]
	global_store_dwordx2 v[52:53], v[48:49], off
	v_lshl_add_u64 v[48:49], v[54:55], 0, v[88:89]
	v_pk_mul_f32 v[44:45], v[44:45], v[42:43] op_sel_hi:[1,0]
	v_pk_mul_f32 v[48:49], v[50:51], v[42:43] op_sel_hi:[1,0]
	v_pk_mul_f32 v[40:41], v[40:41], v[42:43] op_sel_hi:[1,0]
	v_pk_mul_f32 v[36:37], v[36:37], v[42:43] op_sel_hi:[1,0]
	v_pk_mul_f32 v[38:39], v[38:39], v[42:43] op_sel_hi:[1,0]
	s_and_b64 vcc, exec, s[38:39]
	s_nop 0
	v_mov_b64_e32 v[58:59], v[220:221]
	v_mov_b64_e32 v[60:61], v[222:223]
	v_mov_b64_e32 v[62:63], v[236:237]
	v_mov_b64_e32 v[64:65], v[238:239]
	v_pk_add_f32 v[50:51], v[64:65], 1.0 op_sel_hi:[1,0]
	v_pk_add_f32 v[62:63], v[62:63], 1.0 op_sel_hi:[1,0]
	v_pk_fma_f32 v[48:49], v[50:51], v[48:49], v[60:61]
	v_pk_fma_f32 v[44:45], v[62:63], v[44:45], v[58:59]
	s_nop 0
	v_cvt_pk_bf16_f32 v44, v44, v45
	v_cvt_pk_bf16_f32 v45, v48, v49
	global_store_dwordx2 v[52:53], v[44:45], off offset:512
	v_lshl_add_u64 v[44:45], v[54:55], 0, v[90:91]
	v_pk_mul_f32 v[44:45], v[46:47], v[42:43] op_sel_hi:[1,0]
	s_nop 0
	v_mov_b64_e32 v[48:49], v[224:225]
	v_mov_b64_e32 v[50:51], v[226:227]
	v_mov_b64_e32 v[58:59], v[240:241]
	v_mov_b64_e32 v[60:61], v[242:243]
	v_pk_add_f32 v[46:47], v[60:61], 1.0 op_sel_hi:[1,0]
	v_pk_add_f32 v[58:59], v[58:59], 1.0 op_sel_hi:[1,0]
	v_pk_fma_f32 v[44:45], v[46:47], v[44:45], v[50:51]
	v_pk_fma_f32 v[40:41], v[58:59], v[40:41], v[48:49]
	s_nop 0
	v_cvt_pk_bf16_f32 v40, v40, v41
	v_cvt_pk_bf16_f32 v41, v44, v45
	global_store_dwordx2 v[52:53], v[40:41], off offset:1024
	v_lshl_add_u64 v[40:41], v[54:55], 0, v[92:93]
	s_nop 0
	v_mov_b64_e32 v[44:45], v[228:229]
	v_mov_b64_e32 v[46:47], v[230:231]
	v_mov_b64_e32 v[48:49], v[244:245]
	v_mov_b64_e32 v[50:51], v[246:247]
	v_pk_add_f32 v[40:41], v[50:51], 1.0 op_sel_hi:[1,0]
	v_pk_add_f32 v[42:43], v[48:49], 1.0 op_sel_hi:[1,0]
	v_pk_fma_f32 v[38:39], v[40:41], v[38:39], v[46:47]
	v_pk_fma_f32 v[36:37], v[42:43], v[36:37], v[44:45]
	s_nop 0
	v_cvt_pk_bf16_f32 v36, v36, v37
	v_cvt_pk_bf16_f32 v37, v38, v39
	global_store_dwordx2 v[52:53], v[36:37], off offset:1536
	s_cbranch_vccnz .LBB0_110
	v_add_f32_e32 v15, v32, v33
	v_add_f32_e32 v19, v34, v35
	v_add_f32_e32 v15, v15, v19
	v_add_f32_e32 v19, v28, v29
	v_add_f32_e32 v36, v30, v31
	v_add_f32_e32 v15, 0, v15
	v_add_f32_e32 v19, v19, v36
	v_add_f32_e32 v15, v19, v15
	v_add_f32_e32 v19, v24, v25
	v_add_f32_e32 v36, v26, v27
	v_add_f32_e32 v19, v19, v36
	v_add_f32_e32 v15, v19, v15
	v_add_f32_e32 v19, v20, v21
	v_add_f32_e32 v36, v22, v23
	v_add_f32_e32 v19, v19, v36
	v_add_f32_e32 v15, v19, v15
	v_lshl_add_u64 v[46:47], v[16:17], 0, v[100:101]
	s_nop 0
	v_add_f32_dpp v15, v15, v15 row_ror:8 row_mask:0xf bank_mask:0xf bound_ctrl:1
	s_nop 1
	v_add_f32_dpp v15, v15, v15 row_ror:4 row_mask:0xf bank_mask:0xf bound_ctrl:1
	s_nop 1
	v_add_f32_dpp v15, v15, v15 row_ror:2 row_mask:0xf bank_mask:0xf bound_ctrl:1
	s_nop 1
	v_add_f32_dpp v15, v15, v15 row_ror:1 row_mask:0xf bank_mask:0xf bound_ctrl:1
	v_mov_b32_e32 v19, v15
	s_nop 1
	v_permlane16_swap_b32_e32 v15, v19
	v_add_f32_e32 v15, v15, v19
	v_mov_b32_e32 v19, v15
	s_nop 1
	v_permlane32_swap_b32_e32 v15, v19
	v_add_f32_e32 v15, v15, v19
	v_fmamk_f32 v35, v15, 0xba800000, v35
	v_fmac_f32_e32 v33, 0xba800000, v15
	v_fmamk_f32 v34, v15, 0xba800000, v34
	v_fmamk_f32 v32, v15, 0xba800000, v32
	v_mul_f32_e32 v19, v33, v33
	v_mul_f32_e32 v36, v35, v35
	v_fmac_f32_e32 v19, v32, v32
	v_fmac_f32_e32 v36, v34, v34
	v_fmamk_f32 v31, v15, 0xba800000, v31
	v_fmac_f32_e32 v29, 0xba800000, v15
	v_add_f32_e32 v19, v19, v36
	v_fmamk_f32 v30, v15, 0xba800000, v30
	v_fmamk_f32 v28, v15, 0xba800000, v28
	v_mul_f32_e32 v36, v29, v29
	v_mul_f32_e32 v37, v31, v31
	v_fmac_f32_e32 v36, v28, v28
	v_fmac_f32_e32 v37, v30, v30
	v_add_f32_e32 v36, v36, v37
	v_fmamk_f32 v27, v15, 0xba800000, v27
	v_fmac_f32_e32 v25, 0xba800000, v15
	v_add_f32_e32 v19, v19, v36
	v_fmamk_f32 v26, v15, 0xba800000, v26
	v_fmamk_f32 v24, v15, 0xba800000, v24
	v_mul_f32_e32 v36, v25, v25
	v_mul_f32_e32 v37, v27, v27
	v_fmac_f32_e32 v36, v24, v24
	v_fmac_f32_e32 v37, v26, v26
	v_add_f32_e32 v36, v36, v37
	v_fmamk_f32 v23, v15, 0xba800000, v23
	v_fmac_f32_e32 v21, 0xba800000, v15
	v_add_f32_e32 v19, v36, v19
	v_fmamk_f32 v22, v15, 0xba800000, v22
	v_fmamk_f32 v20, v15, 0xba800000, v20
	v_mul_f32_e32 v15, v21, v21
	v_mul_f32_e32 v36, v23, v23
	v_fmac_f32_e32 v15, v20, v20
	v_fmac_f32_e32 v36, v22, v22
	v_add_f32_e32 v15, v15, v36
	v_add_f32_e32 v15, v15, v19
	s_nop 1
	v_add_f32_dpp v15, v15, v15 row_ror:8 row_mask:0xf bank_mask:0xf bound_ctrl:1
	s_nop 1
	v_add_f32_dpp v15, v15, v15 row_ror:4 row_mask:0xf bank_mask:0xf bound_ctrl:1
	s_nop 1
	v_add_f32_dpp v15, v15, v15 row_ror:2 row_mask:0xf bank_mask:0xf bound_ctrl:1
	s_nop 1
	v_add_f32_dpp v15, v15, v15 row_ror:1 row_mask:0xf bank_mask:0xf bound_ctrl:1
	v_mov_b32_e32 v19, v15
	s_nop 1
	v_permlane16_swap_b32_e32 v15, v19
	v_add_f32_e32 v15, v15, v19
	v_mov_b32_e32 v19, v15
	s_nop 1
	v_permlane32_swap_b32_e32 v15, v19
	v_add_f32_e32 v15, v15, v19
	v_fmamk_f32 v15, v15, 0x3a800000, v196
	v_cmp_gt_f32_e32 vcc, s22, v15
	v_mul_f32_e32 v19, 0x4b800000, v15
	s_nop 0
	v_cndmask_b32_e32 v15, v15, v19, vcc
	v_rsq_f32_e32 v15, v15
	s_nop 0
	v_mul_f32_e32 v19, 0x45800000, v15
	v_cndmask_b32_e32 v36, v15, v19, vcc
	v_pk_mul_f32 v[32:33], v[32:33], v[36:37] op_sel_hi:[1,0]
	v_pk_mul_f32 v[34:35], v[34:35], v[36:37] op_sel_hi:[1,0]
	s_nop 0
	v_mov_b64_e32 v[38:39], v[138:139]
	v_mov_b64_e32 v[40:41], v[140:141]
	v_mov_b64_e32 v[42:43], v[154:155]
	v_mov_b64_e32 v[44:45], v[156:157]
	v_pk_fma_f32 v[32:33], v[38:39], v[32:33], v[42:43]
	v_pk_fma_f32 v[34:35], v[40:41], v[34:35], v[44:45]
	global_store_dwordx4 v[46:47], v[32:35], off nt
	v_pk_mul_f32 v[30:31], v[30:31], v[36:37] op_sel_hi:[1,0]
	v_pk_mul_f32 v[28:29], v[28:29], v[36:37] op_sel_hi:[1,0]
	v_pk_mul_f32 v[26:27], v[26:27], v[36:37] op_sel_hi:[1,0]
	v_pk_mul_f32 v[24:25], v[24:25], v[36:37] op_sel_hi:[1,0]
	v_pk_mul_f32 v[22:23], v[22:23], v[36:37] op_sel_hi:[1,0]
	v_pk_mul_f32 v[20:21], v[20:21], v[36:37] op_sel_hi:[1,0]
	s_nop 0
	v_mov_b64_e32 v[38:39], v[142:143]
	v_mov_b64_e32 v[40:41], v[144:145]
	v_mov_b64_e32 v[42:43], v[158:159]
	v_mov_b64_e32 v[44:45], v[160:161]
	v_pk_fma_f32 v[28:29], v[38:39], v[28:29], v[42:43]
	v_pk_fma_f32 v[30:31], v[40:41], v[30:31], v[44:45]
	global_store_dwordx4 v[46:47], v[28:31], off offset:1024 nt
	s_nop 0
	v_mov_b64_e32 v[38:39], v[146:147]
	v_mov_b64_e32 v[40:41], v[148:149]
	v_mov_b64_e32 v[42:43], v[162:163]
	v_mov_b64_e32 v[44:45], v[164:165]
	v_pk_fma_f32 v[24:25], v[38:39], v[24:25], v[42:43]
	v_pk_fma_f32 v[26:27], v[40:41], v[26:27], v[44:45]
	global_store_dwordx4 v[46:47], v[24:27], off offset:2048 nt
	s_nop 0
	v_mov_b64_e32 v[38:39], v[150:151]
	v_mov_b64_e32 v[40:41], v[152:153]
	v_mov_b64_e32 v[42:43], v[166:167]
	v_mov_b64_e32 v[44:45], v[168:169]
	v_pk_fma_f32 v[20:21], v[38:39], v[20:21], v[42:43]
	v_pk_fma_f32 v[22:23], v[40:41], v[22:23], v[44:45]
	global_store_dwordx4 v[46:47], v[20:23], off offset:3072 nt
	s_branch .LBB0_110
